# first 7 packed row-sum adds per half replaced by 14 scalar adds in the PV MFMA gaps
# baseline (speedup 1.0000x reference)
.LBB0_895:
	ds_read_b128 v[124:127], v201 offset:12288
	ds_read_b128 v[128:131], v201 offset:13312
	ds_read_b128 v[136:139], v201 offset:15360
	ds_read_b128 v[140:143], v201 offset:14336
	ds_read_b128 v[148:151], v201 offset:18432
	ds_read_b128 v[152:155], v201 offset:19456
	ds_read_b128 v[204:207], v201 offset:21504
	ds_read_b128 v[208:211], v201 offset:20480
	s_waitcnt lgkmcnt(7)
	v_mfma_f32_16x16x32_bf16 v[132:135], v[124:127], v[12:15], v[44:47]
	v_exp_f32_e32 v195, v84
	v_exp_f32_e32 v194, v88
	v_mfma_f32_16x16x32_bf16 v[124:127], v[124:127], v[16:19], v[48:51]
	v_exp_f32_e32 v88, v91
	v_exp_f32_e32 v84, v81
	s_waitcnt lgkmcnt(3)
	v_mfma_f32_16x16x32_bf16 v[190:193], v[148:151], v[12:15], v[44:47]
	v_exp_f32_e32 v81, v78
	v_exp_f32_e32 v79, v79
	v_mfma_f32_16x16x32_bf16 v[148:151], v[148:151], v[16:19], v[48:51]
	v_exp_f32_e32 v78, v83
	v_exp_f32_e32 v61, v61
	v_mfma_f32_16x16x32_bf16 v[144:147], v[136:139], v[12:15], v[44:47]
	v_exp_f32_e32 v63, v63
	v_exp_f32_e32 v83, v64
	v_mfma_f32_16x16x32_bf16 v[136:139], v[136:139], v[16:19], v[48:51]
	v_exp_f32_e32 v64, v74
	v_exp_f32_e32 v67, v67
	s_waitcnt lgkmcnt(1)
	v_mfma_f32_16x16x32_bf16 v[212:215], v[204:207], v[12:15], v[44:47]
	v_exp_f32_e32 v250, v90
	v_mfma_f32_16x16x32_bf16 v[204:207], v[204:207], v[16:19], v[48:51]
	v_mfma_f32_16x16x32_bf16 v[132:135], v[128:131], v[4:7], v[132:135]
	v_mfma_f32_16x16x32_bf16 v[124:127], v[128:131], v[20:23], v[124:127]
	ds_read_b128 v[128:131], v201 offset:16384
	ds_read_b128 v[216:219], v201 offset:17408
	v_mfma_f32_16x16x32_bf16 v[220:223], v[152:155], v[20:23], v[148:151]
	v_exp_f32_e32 v249, v85
	v_exp_f32_e32 v248, v89
	v_exp_f32_e32 v251, v86
	ds_read_b128 v[148:151], v201 offset:22528
	ds_read_b128 v[224:227], v201 offset:23552
	s_waitcnt lgkmcnt(3)
	v_mfma_f32_16x16x32_bf16 v[144:147], v[128:131], v[4:7], v[144:147]
	v_exp_f32_e32 v89, v87
	v_exp_f32_e32 v87, v76
	v_mfma_f32_16x16x32_bf16 v[128:131], v[128:131], v[20:23], v[136:139]
	v_exp_f32_e32 v86, v80
	s_waitcnt lgkmcnt(1)
	v_mfma_f32_16x16x32_bf16 v[204:207], v[148:151], v[20:23], v[204:207]
	v_exp_f32_e32 v85, v77
	v_exp_f32_e32 v80, v82
	v_mfma_f32_16x16x32_bf16 v[136:139], v[152:155], v[4:7], v[190:193]
	v_exp_f32_e32 v77, v60
	v_mfma_f32_16x16x32_bf16 v[212:215], v[148:151], v[4:7], v[212:215]
	v_exp_f32_e32 v76, v68
	v_exp_f32_e32 v60, v69
	v_mfma_f32_16x16x32_bf16 v[148:151], v[140:143], v[8:11], v[132:135]
	v_exp_f32_e32 v69, v62
	v_mfma_f32_16x16x32_bf16 v[152:155], v[140:143], v[24:27], v[124:127]
	v_exp_f32_e32 v68, v70
	v_exp_f32_e32 v62, v71
	v_mfma_f32_16x16x32_bf16 v[140:143], v[216:219], v[8:11], v[144:147]
	v_exp_f32_e32 v82, v72
	v_mfma_f32_16x16x32_bf16 v[144:147], v[216:219], v[24:27], v[128:131]
	v_exp_f32_e32 v71, v65
	v_exp_f32_e32 v70, v73
	s_waitcnt lgkmcnt(0)
	v_mfma_f32_16x16x32_bf16 v[128:131], v[224:227], v[24:27], v[204:207]
	v_exp_f32_e32 v65, v66
	ds_read_b128 v[204:207], v200 offset:24576
	v_mfma_f32_16x16x32_bf16 v[132:135], v[208:211], v[8:11], v[136:139]
	v_exp_f32_e32 v66, v75
	v_cvt_pk_bf16_f32 v90, v77, v61
	v_mfma_f32_16x16x32_bf16 v[136:139], v[208:211], v[24:27], v[220:223]
	v_cvt_pk_bf16_f32 v208, v195, v249
	v_cvt_pk_bf16_f32 v209, v251, v89
	v_cvt_pk_bf16_f32 v210, v87, v85
	v_mfma_f32_16x16x32_bf16 v[124:127], v[224:227], v[8:11], v[212:215]
	v_cvt_pk_bf16_f32 v211, v81, v79
	ds_read_b128 v[216:219], v200 offset:26624
	ds_read_b128 v[220:223], v200 offset:25600
	v_cvt_pk_bf16_f32 v212, v194, v248
	v_cvt_pk_bf16_f32 v213, v250, v88
	v_cvt_pk_bf16_f32 v214, v86, v84
	v_cvt_pk_bf16_f32 v215, v80, v78
	s_waitcnt lgkmcnt(2)
	v_mfma_f32_16x16x32_bf16 v[120:123], v[204:207], v[208:211], v[120:123]
	v_cvt_pk_bf16_f32 v91, v69, v63
	v_add_f32_e32 v236, v194, v86
	v_mfma_f32_16x16x32_bf16 v[104:107], v[204:207], v[212:215], v[104:107]
	v_add_f32_e32 v237, v195, v87
	v_add_f32_e32 v238, v248, v84
	ds_read_b128 v[204:207], v200 offset:28672
	ds_read_b128 v[224:227], v200 offset:27648
	s_waitcnt lgkmcnt(3)
	v_mfma_f32_16x16x32_bf16 v[228:231], v[216:219], v[208:211], v[116:119]
	v_add_f32_e32 v239, v249, v85
	v_add_f32_e32 v240, v80, v250
	v_add_f32_e32 v241, v81, v251
	v_mfma_f32_16x16x32_bf16 v[100:103], v[216:219], v[212:215], v[100:103]
	v_add_f32_e32 v242, v78, v88
	v_add_f32_e32 v243, v79, v89
	ds_read_b128 v[116:119], v200 offset:30720
	ds_read_b128 v[216:219], v200 offset:29696
	s_waitcnt lgkmcnt(3)
	v_mfma_f32_16x16x32_bf16 v[232:235], v[204:207], v[208:211], v[112:115]
	v_add_f32_e32 v236, v236, v76
	v_add_f32_e32 v237, v237, v77
	v_mfma_f32_16x16x32_bf16 v[96:99], v[204:207], v[212:215], v[96:99]
	v_add_f32_e32 v238, v60, v238
	v_add_f32_e32 v239, v61, v239
	ds_read_b128 v[204:207], v200 offset:31744
	s_waitcnt lgkmcnt(2)
	v_mfma_f32_16x16x32_bf16 v[208:211], v[116:119], v[208:211], v[108:111]
	v_add_f32_e32 v240, v68, v240
	v_add_f32_e32 v241, v69, v241
	v_mfma_f32_16x16x32_bf16 v[72:75], v[116:119], v[212:215], v[92:95]
	v_cvt_pk_bf16_f32 v212, v76, v60
	v_cvt_pk_bf16_f32 v213, v68, v62
	v_cvt_pk_bf16_f32 v214, v82, v70
	v_cvt_pk_bf16_f32 v92, v83, v71
	v_cvt_pk_bf16_f32 v93, v65, v67
	v_cvt_pk_bf16_f32 v215, v64, v66
	s_nop 0
	v_mfma_f32_16x16x32_bf16 v[120:123], v[220:223], v[90:93], v[120:123]
	v_mfma_f32_16x16x32_bf16 v[116:119], v[220:223], v[212:215], v[104:107]
	v_max3_f32 v244, v152, v153, v154
	v_max3_f32 v245, v148, v149, v150
	v_mfma_f32_16x16x32_bf16 v[112:115], v[224:227], v[90:93], v[228:231]
	v_max3_f32 v244, v244, v155, v144
	v_max3_f32 v245, v245, v151, v140
	v_mfma_f32_16x16x32_bf16 v[108:111], v[224:227], v[212:215], v[100:103]
	v_max3_f32 v244, v244, v145, v146
	v_max3_f32 v245, v245, v141, v142
	s_waitcnt lgkmcnt(1)
	v_mfma_f32_16x16x32_bf16 v[104:107], v[216:219], v[90:93], v[232:235]
	v_max3_f32 v244, v244, v147, v136
	v_max3_f32 v245, v245, v143, v132
	v_mfma_f32_16x16x32_bf16 v[100:103], v[216:219], v[212:215], v[96:99]
	v_max3_f32 v244, v244, v137, v138
	v_max3_f32 v245, v245, v133, v134
	s_waitcnt lgkmcnt(0)
	v_mfma_f32_16x16x32_bf16 v[92:95], v[204:207], v[90:93], v[208:211]
	v_max3_f32 v244, v244, v139, v128
	v_max3_f32 v245, v245, v135, v124
	v_mfma_f32_16x16x32_bf16 v[96:99], v[204:207], v[212:215], v[72:75]
	v_max3_f32 v244, v244, v129, v130
	v_max3_f32 v245, v245, v125, v126
	s_waitcnt vmcnt(0)
	ds_write_b128 v197, v[52:55]
	s_and_saveexec_b64 s[16:17], s[10:11]
	ds_write_b128 v199, v[28:31]
	s_or_b64 exec, exec, s[16:17]

.LBB0_905:
	v_pk_add_f32 v[242:243], v[62:63], v[242:243]
	v_pk_add_f32 v[236:237], v[236:237], v[82:83]
	v_pk_add_f32 v[238:239], v[70:71], v[238:239]
	v_pk_add_f32 v[240:241], v[64:65], v[240:241]
	v_pk_add_f32 v[242:243], v[66:67], v[242:243]
	v_pk_add_f32 v[238:239], v[236:237], v[238:239]
	v_pk_add_f32 v[242:243], v[240:241], v[242:243]
	v_max_f32_e32 v60, v244, v131
	v_pk_add_f32 v[238:239], v[238:239], v[242:243]
	v_max_f32_e32 v61, v245, v127
	v_pk_add_f32 v[184:185], v[184:185], v[238:239]
	v_max_f32_e32 v62, v61, v60
	v_cmp_lt_f32_e32 vcc, s8, v62
	s_cbranch_vccz .LBB0_907
	v_and_b32_e32 v63, 64, v202
	v_xor_b32_e32 v62, 16, v202
	v_add_u32_e32 v63, 64, v63
	v_cmp_lt_i32_e32 vcc, v62, v63
	v_xor_b32_e32 v65, 32, v202
	s_nop 0
	v_cndmask_b32_e32 v62, v202, v62, vcc
	v_lshlrev_b32_e32 v62, 2, v62
	ds_bpermute_b32 v64, v62, v61
	ds_bpermute_b32 v62, v62, v60
	v_cmp_lt_i32_e32 vcc, v65, v63
	v_max_f32_e32 v61, v61, v61
	v_max_f32_e32 v60, v60, v60
	s_waitcnt lgkmcnt(1)
	v_max_f32_e32 v64, v64, v64
	v_cndmask_b32_e32 v63, v202, v65, vcc
	v_max_f32_e32 v61, v61, v64
	v_lshlrev_b32_e32 v63, 2, v63
	s_waitcnt lgkmcnt(0)
	v_max_f32_e32 v62, v62, v62
	ds_bpermute_b32 v64, v63, v61
	v_max_f32_e32 v60, v60, v62
	ds_bpermute_b32 v62, v63, v60
	s_waitcnt lgkmcnt(1)
	v_max_f32_e32 v63, v64, v64
	v_max_f32_e32 v61, v61, v63
	s_waitcnt lgkmcnt(0)
	v_max_f32_e32 v62, v62, v62
	v_max_f32_e32 v60, v60, v62
	v_cmp_lt_f32_e32 vcc, s8, v61
	s_nop 1
	v_cndmask_b32_e32 v61, 0, v61, vcc
	v_cmp_lt_f32_e32 vcc, s8, v60
	v_sub_f32_e32 v148, v148, v61
	v_sub_f32_e32 v149, v149, v61
	v_cndmask_b32_e32 v64, 0, v60, vcc
	v_exp_f32_e64 v60, -v61
	v_exp_f32_e64 v62, -v64
	v_sub_f32_e32 v150, v150, v61
	v_sub_f32_e32 v151, v151, v61
	v_sub_f32_e32 v152, v152, v64
	v_pk_mul_f32 v[118:119], v[118:119], v[62:63] op_sel_hi:[1,0]
	v_pk_mul_f32 v[116:117], v[116:117], v[62:63] op_sel_hi:[1,0]
	v_pk_mul_f32 v[110:111], v[110:111], v[62:63] op_sel_hi:[1,0]
	v_pk_mul_f32 v[108:109], v[108:109], v[62:63] op_sel_hi:[1,0]
	v_pk_mul_f32 v[102:103], v[102:103], v[62:63] op_sel_hi:[1,0]
	v_pk_mul_f32 v[100:101], v[100:101], v[62:63] op_sel_hi:[1,0]
	v_pk_mul_f32 v[98:99], v[98:99], v[62:63] op_sel_hi:[1,0]
	v_pk_mul_f32 v[96:97], v[96:97], v[62:63] op_sel_hi:[1,0]
	v_mov_b32_e32 v63, v60
	v_sub_f32_e32 v153, v153, v64
	v_sub_f32_e32 v154, v154, v64
	v_sub_f32_e32 v155, v155, v64
	v_pk_mul_f32 v[122:123], v[122:123], v[60:61] op_sel_hi:[1,0]
	v_pk_mul_f32 v[120:121], v[120:121], v[60:61] op_sel_hi:[1,0]
	v_sub_f32_e32 v140, v140, v61
	v_sub_f32_e32 v141, v141, v61
	v_sub_f32_e32 v142, v142, v61
	v_sub_f32_e32 v143, v143, v61
	v_sub_f32_e32 v144, v144, v64
	v_sub_f32_e32 v145, v145, v64
	v_sub_f32_e32 v146, v146, v64
	v_sub_f32_e32 v147, v147, v64
	v_pk_mul_f32 v[114:115], v[114:115], v[60:61] op_sel_hi:[1,0]
	v_pk_mul_f32 v[112:113], v[112:113], v[60:61] op_sel_hi:[1,0]
	v_sub_f32_e32 v132, v132, v61
	v_sub_f32_e32 v133, v133, v61
	v_sub_f32_e32 v134, v134, v61
	v_sub_f32_e32 v135, v135, v61
	v_sub_f32_e32 v136, v136, v64
	v_sub_f32_e32 v137, v137, v64
	v_sub_f32_e32 v138, v138, v64
	v_sub_f32_e32 v139, v139, v64
	v_pk_mul_f32 v[106:107], v[106:107], v[60:61] op_sel_hi:[1,0]
	v_pk_mul_f32 v[104:105], v[104:105], v[60:61] op_sel_hi:[1,0]
	v_sub_f32_e32 v124, v124, v61
	v_sub_f32_e32 v125, v125, v61
	v_sub_f32_e32 v126, v126, v61
	v_sub_f32_e32 v127, v127, v61
	v_sub_f32_e32 v128, v128, v64
	v_sub_f32_e32 v129, v129, v64
	v_sub_f32_e32 v130, v130, v64
	v_sub_f32_e32 v131, v131, v64
	v_pk_mul_f32 v[94:95], v[94:95], v[60:61] op_sel_hi:[1,0]
	v_pk_mul_f32 v[92:93], v[92:93], v[60:61] op_sel_hi:[1,0]
	v_pk_mul_f32 v[184:185], v[184:185], v[62:63]
	v_sub_f32_e32 v47, v47, v61
	v_sub_f32_e32 v46, v46, v61
	v_sub_f32_e32 v45, v45, v61
	v_sub_f32_e32 v44, v44, v61
	v_sub_f32_e32 v51, v51, v64
	v_sub_f32_e32 v50, v50, v64
	v_sub_f32_e32 v49, v49, v64
	v_sub_f32_e32 v48, v48, v64
.LBB0_907:
	ds_read_b128 v[60:63], v201
	ds_read_b128 v[64:67], v201 offset:1024
	ds_read_b128 v[72:75], v201 offset:3072
	ds_read_b128 v[76:79], v201 offset:2048
	ds_read_b128 v[84:87], v201 offset:6144
	ds_read_b128 v[88:91], v201 offset:7168
	ds_read_b128 v[190:193], v201 offset:9216
	ds_read_b128 v[204:207], v201 offset:8192
	s_waitcnt lgkmcnt(7)
	v_mfma_f32_16x16x32_bf16 v[68:71], v[60:63], v[12:15], v[44:47]
	v_exp_f32_e32 v149, v149
	v_exp_f32_e32 v151, v151
	v_mfma_f32_16x16x32_bf16 v[60:63], v[60:63], v[16:19], v[48:51]
	v_exp_f32_e32 v143, v143
	v_exp_f32_e32 v133, v133
	s_waitcnt lgkmcnt(3)
	v_mfma_f32_16x16x32_bf16 v[186:189], v[84:87], v[12:15], v[44:47]
	v_exp_f32_e32 v135, v135
	v_exp_f32_e32 v127, v127
	v_mfma_f32_16x16x32_bf16 v[84:87], v[84:87], v[16:19], v[48:51]
	v_exp_f32_e32 v249, v148
	v_exp_f32_e32 v248, v152
	v_mfma_f32_16x16x32_bf16 v[80:83], v[72:75], v[12:15], v[44:47]
	v_exp_f32_e32 v148, v153
	v_mfma_f32_16x16x32_bf16 v[72:75], v[72:75], v[16:19], v[48:51]
	v_exp_f32_e32 v153, v150
	v_exp_f32_e32 v152, v154
	s_waitcnt lgkmcnt(1)
	v_mfma_f32_16x16x32_bf16 v[208:211], v[190:193], v[12:15], v[44:47]
	v_exp_f32_e32 v150, v155
	v_mfma_f32_16x16x32_bf16 v[190:193], v[190:193], v[16:19], v[48:51]
	v_exp_f32_e32 v155, v141
	v_exp_f32_e32 v154, v145
	v_mfma_f32_16x16x32_bf16 v[68:71], v[64:67], v[4:7], v[68:71]
	v_exp_f32_e32 v145, v142
	v_mfma_f32_16x16x32_bf16 v[60:63], v[64:67], v[20:23], v[60:63]
	v_exp_f32_e32 v142, v147
	ds_read_b128 v[64:67], v201 offset:4096
	ds_read_b128 v[212:215], v201 offset:5120
	v_mfma_f32_16x16x32_bf16 v[216:219], v[88:91], v[20:23], v[84:87]
	v_exp_f32_e32 v141, v132
	v_exp_f32_e32 v132, v137
	v_exp_f32_e32 v251, v140
	ds_read_b128 v[84:87], v201 offset:10240
	ds_read_b128 v[220:223], v201 offset:11264
	s_waitcnt lgkmcnt(3)
	v_mfma_f32_16x16x32_bf16 v[80:83], v[64:67], v[4:7], v[80:83]
	v_exp_f32_e32 v250, v144
	v_mfma_f32_16x16x32_bf16 v[64:67], v[64:67], v[20:23], v[72:75]
	v_exp_f32_e32 v144, v146
	v_exp_f32_e32 v140, v136
	v_mfma_f32_16x16x32_bf16 v[72:75], v[88:91], v[4:7], v[186:189]
	v_exp_f32_e32 v137, v134
	s_waitcnt lgkmcnt(1)
	v_mfma_f32_16x16x32_bf16 v[188:191], v[84:87], v[20:23], v[190:193]
	v_exp_f32_e32 v136, v138
	v_exp_f32_e32 v134, v139
	v_mfma_f32_16x16x32_bf16 v[88:91], v[76:79], v[24:27], v[60:63]
	v_exp_f32_e32 v139, v124
	v_mfma_f32_16x16x32_bf16 v[60:63], v[204:207], v[8:11], v[72:75]
	v_exp_f32_e32 v138, v128
	s_waitcnt lgkmcnt(0)
	v_mfma_f32_16x16x32_bf16 v[72:75], v[220:223], v[24:27], v[188:191]
	v_exp_f32_e32 v147, v125
	ds_read_b128 v[190:193], v200 offset:32768
	v_mfma_f32_16x16x32_bf16 v[208:211], v[84:87], v[4:7], v[208:211]
	v_exp_f32_e32 v146, v129
	v_mfma_f32_16x16x32_bf16 v[84:87], v[76:79], v[8:11], v[68:71]
	v_exp_f32_e32 v125, v126
	v_mfma_f32_16x16x32_bf16 v[76:79], v[212:215], v[8:11], v[80:83]
	v_exp_f32_e32 v124, v130
	v_mfma_f32_16x16x32_bf16 v[80:83], v[212:215], v[24:27], v[64:67]
	v_exp_f32_e32 v126, v131
	v_mfma_f32_16x16x32_bf16 v[68:71], v[204:207], v[24:27], v[216:219]
	ds_read_b128 v[212:215], v200 offset:34816
	s_nop 1
	ds_read_b128 v[216:219], v200 offset:33792
	v_cvt_pk_bf16_f32 v204, v249, v149
	v_cvt_pk_bf16_f32 v205, v153, v151
	v_mfma_f32_16x16x32_bf16 v[64:67], v[220:223], v[8:11], v[208:211]
	v_cvt_pk_bf16_f32 v206, v251, v155
	v_cvt_pk_bf16_f32 v207, v145, v143
	v_cvt_pk_bf16_f32 v208, v248, v148
	v_cvt_pk_bf16_f32 v209, v152, v150
	v_cvt_pk_bf16_f32 v210, v250, v154
	v_cvt_pk_bf16_f32 v211, v144, v142
	s_waitcnt lgkmcnt(2)
	v_mfma_f32_16x16x32_bf16 v[120:123], v[190:193], v[204:207], v[120:123]
	v_add_f32_e32 v236, v248, v250
	v_add_f32_e32 v237, v249, v251
	v_mfma_f32_16x16x32_bf16 v[116:119], v[190:193], v[208:211], v[116:119]
	v_add_f32_e32 v238, v148, v154
	v_add_f32_e32 v239, v149, v155
	ds_read_b128 v[190:193], v200 offset:36864
	ds_read_b128 v[220:223], v200 offset:35840
	s_waitcnt lgkmcnt(3)
	v_mfma_f32_16x16x32_bf16 v[112:115], v[212:215], v[204:207], v[112:115]
	v_add_f32_e32 v240, v144, v152
	v_add_f32_e32 v241, v145, v153
	v_mfma_f32_16x16x32_bf16 v[108:111], v[212:215], v[208:211], v[108:111]
	v_add_f32_e32 v242, v142, v150
	v_add_f32_e32 v243, v143, v151
	ds_read_b128 v[212:215], v200 offset:38912
	ds_read_b128 v[224:227], v200 offset:37888
	ds_read_b128 v[232:235], v200 offset:39936
	s_waitcnt lgkmcnt(4)
	v_mfma_f32_16x16x32_bf16 v[228:231], v[190:193], v[204:207], v[104:107]
	v_add_f32_e32 v236, v236, v140
	v_add_f32_e32 v237, v237, v141
	v_mfma_f32_16x16x32_bf16 v[190:193], v[190:193], v[208:211], v[100:103]
	v_add_f32_e32 v238, v238, v132
	v_add_f32_e32 v239, v239, v133
	s_waitcnt lgkmcnt(2)
	v_mfma_f32_16x16x32_bf16 v[92:95], v[212:215], v[204:207], v[92:95]
	v_add_f32_e32 v240, v136, v240
	v_add_f32_e32 v241, v137, v241
	v_cvt_pk_bf16_f32 v204, v141, v133
	v_cvt_pk_bf16_f32 v205, v137, v135
	v_cvt_pk_bf16_f32 v206, v139, v147
	v_mfma_f32_16x16x32_bf16 v[128:131], v[212:215], v[208:211], v[96:99]
	v_cvt_pk_bf16_f32 v207, v125, v127
	v_cvt_pk_bf16_f32 v208, v140, v132
	v_cvt_pk_bf16_f32 v209, v136, v134
	v_cvt_pk_bf16_f32 v210, v138, v146
	v_cvt_pk_bf16_f32 v211, v124, v126
	v_mfma_f32_16x16x32_bf16 v[120:123], v[216:219], v[204:207], v[120:123]
	s_nop 0
	v_mfma_f32_16x16x32_bf16 v[104:107], v[216:219], v[208:211], v[116:119]
	v_max3_f32 v246, v88, v89, v90
	v_max3_f32 v247, v84, v85, v86
	v_mfma_f32_16x16x32_bf16 v[116:119], v[220:223], v[204:207], v[112:115]
	v_max3_f32 v246, v246, v91, v80
	v_max3_f32 v247, v247, v87, v76
	v_mfma_f32_16x16x32_bf16 v[100:103], v[220:223], v[208:211], v[108:111]
	v_max3_f32 v246, v246, v81, v82
	v_max3_f32 v247, v247, v77, v78
	s_waitcnt lgkmcnt(1)
	v_mfma_f32_16x16x32_bf16 v[112:115], v[224:227], v[204:207], v[228:231]
	v_max3_f32 v246, v246, v83, v68
	v_max3_f32 v247, v247, v79, v60
	v_mfma_f32_16x16x32_bf16 v[96:99], v[224:227], v[208:211], v[190:193]
	v_max3_f32 v246, v246, v69, v70
	v_max3_f32 v247, v247, v61, v62
	s_waitcnt lgkmcnt(0)
	v_mfma_f32_16x16x32_bf16 v[108:111], v[232:235], v[204:207], v[92:95]
	v_max3_f32 v246, v246, v71, v72
	v_max3_f32 v247, v247, v63, v64
	v_mfma_f32_16x16x32_bf16 v[92:95], v[232:235], v[208:211], v[128:131]
	v_max3_f32 v246, v246, v73, v74
	v_max3_f32 v247, v247, v65, v66
	ds_write_b128 v197, v[32:35] offset:12288
	s_and_saveexec_b64 s[16:17], s[10:11]
	ds_write_b128 v199, v[36:39] offset:12288
	s_or_b64 exec, exec, s[16:17]
.LBB0_911:
	ds_write2_b64 v177, v[40:41], v[42:43] offset1:32
	v_pk_add_f32 v[242:243], v[134:135], v[242:243]
	v_pk_add_f32 v[236:237], v[236:237], v[138:139]
	v_pk_add_f32 v[238:239], v[238:239], v[146:147]
	v_pk_add_f32 v[240:241], v[124:125], v[240:241]
	v_pk_add_f32 v[242:243], v[126:127], v[242:243]
	s_add_i32 s26, s26, 2
	v_pk_add_f32 v[240:241], v[240:241], v[242:243]
	v_pk_add_f32 v[236:237], v[236:237], v[238:239]
	v_lshl_add_u64 v[2:3], v[2:3], 0, s[42:43]
	v_pk_add_f32 v[236:237], v[236:237], v[240:241]
	v_lshl_add_u64 v[180:181], v[180:181], 0, s[44:45]
	v_pk_add_f32 v[184:185], v[184:185], v[236:237]
	v_lshl_add_u64 v[182:183], v[182:183], 0, s[46:47]
	s_cmpk_gt_u32 s26, 0x7f
	s_waitcnt lgkmcnt(0)
	s_barrier
	s_cbranch_scc0 .LBB0_887
	s_waitcnt vmcnt(0)
	s_branch .LBB0_857
